# grid barrier: non-leader workgroups poll the cross-XCD release word directly (no forwarding hop through the XCD leader)
# baseline (speedup 1.0000x reference)
.LBB0_99:
	s_or_b64 exec, exec, s[10:11]
	v_cvt_f32_u32_e32 v5, v3
	s_waitcnt vmcnt(0)
	v_readfirstlane_b32 s8, v4
	s_add_u32 s6, s6, 0x2400
	s_addc_u32 s7, s7, 0
	v_rcp_iflag_f32_e32 v5, v5
	v_add_u32_e32 v6, s8, v2
	v_mul_f32_e32 v4, 0x4f7ffffe, v5
	v_cvt_u32_f32_e32 v4, v4
	v_sub_u32_e32 v5, 0, v3
	v_mul_lo_u32 v2, v5, v4
	v_mul_hi_u32 v2, v4, v2
	v_add_u32_e32 v2, v4, v2
	v_mul_hi_u32 v2, v6, v2
	v_mul_lo_u32 v4, v2, v3
	v_sub_u32_e32 v4, v6, v4
	v_add_u32_e32 v5, 1, v2
	v_cmp_ge_u32_e32 vcc, v4, v3
	s_nop 1
	v_cndmask_b32_e32 v2, v2, v5, vcc
	v_sub_u32_e32 v5, v4, v3
	v_cndmask_b32_e32 v4, v4, v5, vcc
	v_add_u32_e32 v5, 1, v2
	v_cmp_ge_u32_e32 vcc, v4, v3
	v_add_u32_e32 v4, 1, v6
	s_nop 0
	v_cndmask_b32_e32 v2, v2, v5, vcc
	v_mul_lo_u32 v5, v3, v2
	v_add_u32_e32 v3, v5, v3
	v_cmp_ne_u32_e32 vcc, v4, v3
	s_and_saveexec_b64 s[8:9], vcc
	s_xor_b64 s[8:9], exec, s[8:9]
	s_cbranch_execz .LBB0_113
	s_waitcnt lgkmcnt(0)
	v_mov_b32_e32 v1, 0
	v_readlane_b32 s6, v254, 6
	v_readlane_b32 s7, v254, 7
	s_nop 0
	s_add_u32 s6, s6, 0x3500
	s_addc_u32 s7, s7, 0
	global_load_dword v3, v1, s[6:7] sc1
	s_waitcnt vmcnt(0)
	v_cmp_eq_u32_e32 vcc, v3, v2
	s_and_saveexec_b64 s[10:11], vcc
	s_cbranch_execz .LBB0_112
	s_mov_b32 s22, 1
	s_mov_b64 s[12:13], 0
	s_branch .LBB0_103

.LBB0_636:
	s_or_b64 exec, exec, s[8:9]
	v_cvt_f32_u32_e32 v5, v3
	s_waitcnt vmcnt(0)
	v_readfirstlane_b32 s6, v4
	s_add_u32 s4, s4, 0x2400
	s_addc_u32 s5, s5, 0
	v_rcp_iflag_f32_e32 v5, v5
	v_add_u32_e32 v6, s6, v2
	v_mul_f32_e32 v4, 0x4f7ffffe, v5
	v_cvt_u32_f32_e32 v4, v4
	v_sub_u32_e32 v5, 0, v3
	v_mul_lo_u32 v2, v5, v4
	v_mul_hi_u32 v2, v4, v2
	v_add_u32_e32 v2, v4, v2
	v_mul_hi_u32 v2, v6, v2
	v_mul_lo_u32 v4, v2, v3
	v_sub_u32_e32 v4, v6, v4
	v_add_u32_e32 v5, 1, v2
	v_cmp_ge_u32_e32 vcc, v4, v3
	s_nop 1
	v_cndmask_b32_e32 v2, v2, v5, vcc
	v_sub_u32_e32 v5, v4, v3
	v_cndmask_b32_e32 v4, v4, v5, vcc
	v_add_u32_e32 v5, 1, v2
	v_cmp_ge_u32_e32 vcc, v4, v3
	v_add_u32_e32 v4, 1, v6
	s_nop 0
	v_cndmask_b32_e32 v2, v2, v5, vcc
	v_mul_lo_u32 v5, v3, v2
	v_add_u32_e32 v3, v5, v3
	v_cmp_ne_u32_e32 vcc, v4, v3
	s_and_saveexec_b64 s[6:7], vcc
	s_xor_b64 s[6:7], exec, s[6:7]
	s_cbranch_execz .LBB0_650
	s_waitcnt lgkmcnt(0)
	v_mov_b32_e32 v1, 0
	v_readlane_b32 s4, v254, 6
	v_readlane_b32 s5, v254, 7
	s_nop 0
	s_add_u32 s4, s4, 0x3500
	s_addc_u32 s5, s5, 0
	global_load_dword v3, v1, s[4:5] sc1
	s_waitcnt vmcnt(0)
	v_cmp_eq_u32_e32 vcc, v3, v2
	s_and_saveexec_b64 s[8:9], vcc
	s_cbranch_execz .LBB0_649
	s_mov_b32 s20, 1
	s_mov_b64 s[10:11], 0
	s_branch .LBB0_640
